# first norm_phase gets the hand-written 8-rows-per-wave pipelined fast path (as P5 norm)
# speedup vs baseline: 1.0032x; 1.0032x over previous
.LBB0_197:
	v_mov_b32_e32 v4, v178
	s_lshl_b32 s0, s89, 2
	v_ashrrev_i32_e32 v0, 6, v4
	v_writelane_b32 v237, s0, 50
	v_add_u32_e32 v12, s0, v0
	s_movk_i32 s0, 0x4000
	s_lshl_b32 s20, s26, 2
	v_cmp_gt_i32_e32 vcc, s0, v12
	s_and_saveexec_b64 s[0:1], vcc
	s_cbranch_execz .LBB0_200
	v_lshlrev_b32_e32 v0, 2, v4
	v_and_b32_e32 v6, 0xfc, v0
	v_readlane_b32 s36, v237, 10
	v_lshlrev_b32_e32 v14, 2, v6
	v_readlane_b32 s42, v237, 16
	v_readlane_b32 s43, v237, 17
	v_mbcnt_hi_u32_b32 v5, -1, v28
	v_and_b32_e32 v8, 64, v5
	v_xor_b32_e32 v7, 1, v5
	v_add_u32_e32 v8, 64, v8
	v_cmp_lt_i32_e32 vcc, v7, v8
	global_load_dwordx4 v[0:3], v14, s[42:43]
	v_ashrrev_i32_e32 v13, 31, v12
	v_cndmask_b32_e32 v7, v5, v7, vcc
	v_lshlrev_b32_e32 v29, 2, v7
	v_xor_b32_e32 v7, 2, v5
	v_cmp_lt_i32_e32 vcc, v7, v8
	v_lshlrev_b64 v[18:19], 11, v[12:13]
	s_mov_b64 s[2:3], 0x4c47000
	v_cndmask_b32_e32 v7, v5, v7, vcc
	v_lshlrev_b32_e32 v30, 2, v7
	v_xor_b32_e32 v7, 4, v5
	v_cmp_lt_i32_e32 vcc, v7, v8
	v_readlane_b32 s37, v237, 11
	v_mov_b32_e32 v15, 0
	v_cndmask_b32_e32 v7, v5, v7, vcc
	v_lshlrev_b32_e32 v31, 2, v7
	v_xor_b32_e32 v7, 8, v5
	v_cmp_lt_i32_e32 vcc, v7, v8
	v_or_b32_e32 v10, 0x200, v6
	v_or_b32_e32 v26, 0x300, v6
	v_cndmask_b32_e32 v7, v5, v7, vcc
	v_lshlrev_b32_e32 v32, 2, v7
	v_xor_b32_e32 v7, 16, v5
	v_cmp_lt_i32_e32 vcc, v7, v8
	s_ashr_i32 s21, s20, 31
	s_mov_b64 s[6:7], 0xc00
	v_cndmask_b32_e32 v7, v5, v7, vcc
	v_lshlrev_b32_e32 v33, 2, v7
	v_xor_b32_e32 v7, 32, v5
	v_cmp_lt_i32_e32 vcc, v7, v8
	v_or_b32_e32 v8, 0x100, v6
	v_lshl_add_u64 v[16:17], s[42:43], 0, v[14:15]
	v_cndmask_b32_e32 v5, v5, v7, vcc
	v_and_b32_e32 v7, 63, v4
	v_lshl_or_b32 v18, v7, 3, v18
	v_lshlrev_b32_e32 v34, 2, v5
	v_lshl_add_u64 v[4:5], s[24:25], 0, v[18:19]
	v_lshl_add_u64 v[18:19], v[4:5], 0, s[2:3]
	v_lshlrev_b64 v[4:5], 12, v[12:13]
	v_lshl_or_b32 v4, v7, 4, v4
	v_lshl_add_u64 v[4:5], s[36:37], 0, v[4:5]
	s_lshl_b64 s[2:3], s[20:21], 11
	v_lshl_add_u64 v[20:21], v[4:5], 0, s[6:7]
	s_lshl_b64 s[6:7], s[20:21], 12
	s_mov_b64 s[8:9], 0
	v_mov_b32_e32 v13, 0x358637bd
	s_mov_b32 s12, 0x800000
	s_mov_b64 s[10:11], 0x1000
	v_lshlrev_b32_e32 v14, 2, v6
	v_lshlrev_b32_e32 v22, 2, v8
	v_mov_b32_e32 v23, v15
	v_lshlrev_b32_e32 v24, 2, v10
	v_mov_b32_e32 v25, v15
	v_lshlrev_b32_e32 v26, 2, v26
	v_mov_b32_e32 v27, v15
	s_movk_i32 s13, 0x3fff
	v_readlane_b32 s38, v237, 12
	v_readlane_b32 s39, v237, 13
	v_readlane_b32 s40, v237, 14
	v_readlane_b32 s41, v237, 15
	v_readlane_b32 s44, v237, 18
	v_readlane_b32 s45, v237, 19
	v_readlane_b32 s46, v237, 20
	v_readlane_b32 s47, v237, 21
	v_readlane_b32 s48, v237, 22
	v_readlane_b32 s49, v237, 23
	v_readlane_b32 s50, v237, 24
	v_readlane_b32 s51, v237, 25
	s_cmpk_eq_u32 s20, 0x800
	s_cbranch_scc1 .Lnf0_entry
.LBB0_199:
	global_load_dwordx4 v[8:11], v[20:21], off offset:-3072
	global_load_dwordx4 v[4:7], v[20:21], off offset:-2048
	global_load_dwordx4 v[36:39], v[20:21], off offset:-1024
	global_load_dwordx4 v[40:43], v[20:21], off
	v_ashrrev_i32_e32 v35, 12, v12
	v_mul_i32_i24_e32 v56, 0xc00, v35
	v_ashrrev_i32_e32 v57, 31, v56
	v_lshl_add_u64 v[56:57], v[56:57], 2, s[34:35]
	v_lshl_add_u64 v[72:73], v[56:57], 0, s[10:11]
	v_lshl_add_u64 v[68:69], v[56:57], 0, v[14:15]
	v_lshl_add_u64 v[74:75], v[72:73], 0, v[14:15]
	v_lshl_add_u64 v[76:77], v[72:73], 0, v[22:23]
	v_lshl_add_u64 v[80:81], v[72:73], 0, v[24:25]
	v_lshl_add_u64 v[84:85], v[72:73], 0, v[26:27]
	global_load_dwordx4 v[44:47], v[16:17], off offset:1024
	global_load_dwordx4 v[48:51], v[16:17], off offset:2048
	global_load_dwordx4 v[52:55], v[16:17], off offset:3072
	global_load_dwordx4 v[56:59], v[68:69], off
	global_load_dwordx4 v[60:63], v[68:69], off offset:1024
	global_load_dwordx4 v[64:67], v[68:69], off offset:2048
	s_nop 0
	global_load_dwordx4 v[68:71], v[68:69], off offset:3072
	s_nop 0
	global_load_dwordx4 v[72:75], v[74:75], off
	s_nop 0
	global_load_dwordx4 v[76:79], v[76:77], off
	s_nop 0
	global_load_dwordx4 v[80:83], v[80:81], off
	s_nop 0
	global_load_dwordx4 v[84:87], v[84:85], off
	v_add_u32_e32 v12, s20, v12
	v_cmp_lt_i32_e32 vcc, s13, v12
	s_or_b64 s[8:9], vcc, s[8:9]
	v_lshl_add_u64 v[20:21], v[20:21], 0, s[6:7]
	s_waitcnt vmcnt(14)
	v_mov_b32_e32 v90, v9
	s_waitcnt vmcnt(13)
	v_mov_b32_e32 v91, v5
	v_mov_b32_e32 v88, v8
	v_mov_b32_e32 v89, v4
	s_waitcnt vmcnt(12)
	v_mov_b32_e32 v98, v37
	s_waitcnt vmcnt(11)
	v_mov_b32_e32 v99, v41
	v_pk_mul_f32 v[90:91], v[90:91], v[90:91]
	v_mov_b32_e32 v92, v10
	v_mov_b32_e32 v93, v6
	v_mov_b32_e32 v96, v36
	v_mov_b32_e32 v97, v40
	v_pk_mul_f32 v[98:99], v[98:99], v[98:99]
	v_pk_fma_f32 v[88:89], v[88:89], v[88:89], v[90:91]
	v_mov_b32_e32 v94, v11
	v_mov_b32_e32 v95, v7
	v_mov_b32_e32 v100, v38
	v_mov_b32_e32 v101, v42
	v_pk_fma_f32 v[90:91], v[96:97], v[96:97], v[98:99]
	v_pk_fma_f32 v[88:89], v[92:93], v[92:93], v[88:89]
	v_mov_b32_e32 v102, v39
	v_mov_b32_e32 v103, v43
	v_pk_fma_f32 v[90:91], v[100:101], v[100:101], v[90:91]
	v_pk_fma_f32 v[88:89], v[94:95], v[94:95], v[88:89]
	v_pk_fma_f32 v[90:91], v[102:103], v[102:103], v[90:91]
	v_add_f32_e32 v35, v88, v89
	v_add_f32_e32 v35, v35, v90
	v_add_f32_e32 v35, v35, v91
	ds_bpermute_b32 v88, v29, v35
	s_waitcnt vmcnt(3)
	v_pk_add_f32 v[72:73], v[72:73], 1.0 op_sel_hi:[1,0]
	v_pk_add_f32 v[74:75], v[74:75], 1.0 op_sel_hi:[1,0]
	s_waitcnt vmcnt(2)
	v_pk_add_f32 v[78:79], v[78:79], 1.0 op_sel_hi:[1,0]
	v_pk_add_f32 v[76:77], v[76:77], 1.0 op_sel_hi:[1,0]
	s_waitcnt lgkmcnt(0)
	v_add_f32_e32 v35, v35, v88
	ds_bpermute_b32 v88, v30, v35
	s_waitcnt vmcnt(1)
	v_pk_add_f32 v[82:83], v[82:83], 1.0 op_sel_hi:[1,0]
	v_pk_add_f32 v[80:81], v[80:81], 1.0 op_sel_hi:[1,0]
	s_waitcnt vmcnt(0)
	v_pk_add_f32 v[86:87], v[86:87], 1.0 op_sel_hi:[1,0]
	v_pk_add_f32 v[84:85], v[84:85], 1.0 op_sel_hi:[1,0]
	s_waitcnt lgkmcnt(0)
	v_add_f32_e32 v35, v35, v88
	ds_bpermute_b32 v88, v31, v35
	s_waitcnt lgkmcnt(0)
	v_add_f32_e32 v35, v35, v88
	ds_bpermute_b32 v88, v32, v35
	s_waitcnt lgkmcnt(0)
	v_add_f32_e32 v35, v35, v88
	ds_bpermute_b32 v88, v33, v35
	s_waitcnt lgkmcnt(0)
	v_add_f32_e32 v35, v35, v88
	ds_bpermute_b32 v88, v34, v35
	s_waitcnt lgkmcnt(0)
	v_add_f32_e32 v35, v35, v88
	v_fmamk_f32 v35, v35, 0x3a800000, v13
	v_mul_f32_e32 v88, 0x4b800000, v35
	v_cmp_gt_f32_e32 vcc, s12, v35
	s_nop 1
	v_cndmask_b32_e32 v35, v35, v88, vcc
	v_rsq_f32_e32 v35, v35
	s_nop 0
	v_mul_f32_e32 v88, 0x45800000, v35
	v_cndmask_b32_e32 v88, v35, v88, vcc
	v_pk_mul_f32 v[8:9], v[8:9], v[88:89] op_sel_hi:[1,0]
	v_pk_mul_f32 v[10:11], v[10:11], v[88:89] op_sel_hi:[1,0]
	v_pk_mul_f32 v[6:7], v[6:7], v[88:89] op_sel_hi:[1,0]
	v_pk_mul_f32 v[4:5], v[4:5], v[88:89] op_sel_hi:[1,0]
	v_pk_mul_f32 v[8:9], v[0:1], v[8:9]
	v_pk_mul_f32 v[38:39], v[38:39], v[88:89] op_sel_hi:[1,0]
	v_pk_mul_f32 v[36:37], v[36:37], v[88:89] op_sel_hi:[1,0]
	v_pk_mul_f32 v[42:43], v[42:43], v[88:89] op_sel_hi:[1,0]
	v_pk_mul_f32 v[40:41], v[40:41], v[88:89] op_sel_hi:[1,0]
	v_pk_mul_f32 v[10:11], v[2:3], v[10:11]
	v_pk_mul_f32 v[4:5], v[44:45], v[4:5]
	v_pk_mul_f32 v[6:7], v[46:47], v[6:7]
	v_pk_fma_f32 v[8:9], v[72:73], v[8:9], v[56:57]
	v_pk_mul_f32 v[36:37], v[48:49], v[36:37]
	v_pk_mul_f32 v[38:39], v[50:51], v[38:39]
	v_pk_mul_f32 v[40:41], v[40:41], v[52:53]
	v_pk_mul_f32 v[42:43], v[42:43], v[54:55]
	v_pk_fma_f32 v[10:11], v[74:75], v[10:11], v[58:59]
	v_pk_fma_f32 v[6:7], v[78:79], v[6:7], v[62:63]
	v_pk_fma_f32 v[4:5], v[76:77], v[4:5], v[60:61]
	v_cvt_pk_bf16_f32 v8, v8, v9
	v_cvt_pk_bf16_f32 v9, v10, v11
	v_pk_fma_f32 v[38:39], v[82:83], v[38:39], v[66:67]
	v_pk_fma_f32 v[36:37], v[80:81], v[36:37], v[64:65]
	v_pk_fma_f32 v[42:43], v[42:43], v[86:87], v[70:71]
	v_pk_fma_f32 v[40:41], v[40:41], v[84:85], v[68:69]
	v_cvt_pk_bf16_f32 v4, v4, v5
	v_cvt_pk_bf16_f32 v5, v6, v7
	v_cvt_pk_bf16_f32 v6, v36, v37
	v_cvt_pk_bf16_f32 v7, v38, v39
	v_cvt_pk_bf16_f32 v11, v42, v43
	s_nop 0
	v_cvt_pk_bf16_f32 v10, v40, v41
	global_store_dwordx2 v[18:19], v[8:9], off
	global_store_dwordx2 v[18:19], v[4:5], off offset:512
	global_store_dwordx2 v[18:19], v[6:7], off offset:1024
	global_store_dwordx2 v[18:19], v[10:11], off offset:1536
	v_lshl_add_u64 v[18:19], v[18:19], 0, s[2:3]
	s_andn2_b64 exec, exec, s[8:9]
	s_cbranch_execnz .LBB0_199
	s_branch .LBB0_200
.Lnf0_entry:
	s_waitcnt vmcnt(0)
	v_mov_b32_e32 v176, v13
	s_nop 1
	v_readfirstlane_b32 s36, v12
	v_readfirstlane_b32 s38, v20
	v_readfirstlane_b32 s39, v21
	v_readfirstlane_b32 s40, v16
	v_readfirstlane_b32 s41, v17
	v_readfirstlane_b32 s42, v18
	v_readfirstlane_b32 s43, v19
	v_mov_b32_e32 v2, v14
	v_lshrrev_b32_e32 v1, 1, v2
	s_sub_u32 s38, s38, 0xc00
	s_subb_u32 s39, s39, 0
	s_nop 3
	global_load_dwordx4 v[4:7], v2, s[40:41] offset:0
	global_load_dwordx4 v[8:11], v2, s[40:41] offset:1024
	global_load_dwordx4 v[12:15], v2, s[40:41] offset:2048
	global_load_dwordx4 v[16:19], v2, s[40:41] offset:3072
	s_lshr_b32 s48, s36, 12
	s_mul_i32 s48, s48, 0x3000
	s_add_u32 s44, s34, s48
	s_addc_u32 s45, s35, 0
	s_add_u32 s46, s44, 0x1000
	s_addc_u32 s47, s45, 0
	s_add_i32 s36, s36, 0x1000
	global_load_dwordx4 v[30:33], v2, s[44:45] offset:0
	global_load_dwordx4 v[34:37], v2, s[44:45] offset:1024
	global_load_dwordx4 v[38:41], v2, s[44:45] offset:2048
	global_load_dwordx4 v[42:45], v2, s[44:45] offset:3072
	global_load_dwordx4 v[46:49], v2, s[46:47] offset:0
	global_load_dwordx4 v[50:53], v2, s[46:47] offset:1024
	global_load_dwordx4 v[54:57], v2, s[46:47] offset:2048
	global_load_dwordx4 v[58:61], v2, s[46:47] offset:3072
	global_load_dwordx4 v[62:65], v2, s[38:39] offset:0
	global_load_dwordx4 v[66:69], v2, s[38:39] offset:1024
	global_load_dwordx4 v[70:73], v2, s[38:39] offset:2048
	global_load_dwordx4 v[74:77], v2, s[38:39] offset:3072
	s_add_u32 s38, s38, 0x800000
	s_addc_u32 s39, s39, 0
	global_load_dwordx4 v[78:81], v2, s[38:39] offset:0
	global_load_dwordx4 v[82:85], v2, s[38:39] offset:1024
	global_load_dwordx4 v[86:89], v2, s[38:39] offset:2048
	global_load_dwordx4 v[90:93], v2, s[38:39] offset:3072
	s_add_u32 s38, s38, 0x800000
	s_addc_u32 s39, s39, 0
	s_lshr_b32 s48, s36, 12
	s_mul_i32 s48, s48, 0x3000
	s_add_u32 s44, s34, s48
	s_addc_u32 s45, s35, 0
	s_add_u32 s46, s44, 0x1000
	s_addc_u32 s47, s45, 0
	s_add_i32 s36, s36, 0x1000
	global_load_dwordx4 v[96:99], v2, s[44:45] offset:0
	global_load_dwordx4 v[100:103], v2, s[44:45] offset:1024
	global_load_dwordx4 v[104:107], v2, s[44:45] offset:2048
	global_load_dwordx4 v[108:111], v2, s[44:45] offset:3072
	global_load_dwordx4 v[112:115], v2, s[46:47] offset:0
	global_load_dwordx4 v[116:119], v2, s[46:47] offset:1024
	global_load_dwordx4 v[120:123], v2, s[46:47] offset:2048
	global_load_dwordx4 v[124:127], v2, s[46:47] offset:3072
	global_load_dwordx4 v[128:131], v2, s[38:39] offset:0
	global_load_dwordx4 v[132:135], v2, s[38:39] offset:1024
	global_load_dwordx4 v[136:139], v2, s[38:39] offset:2048
	global_load_dwordx4 v[140:143], v2, s[38:39] offset:3072
	s_add_u32 s38, s38, 0x800000
	s_addc_u32 s39, s39, 0
	global_load_dwordx4 v[144:147], v2, s[38:39] offset:0
	global_load_dwordx4 v[148:151], v2, s[38:39] offset:1024
	global_load_dwordx4 v[152:155], v2, s[38:39] offset:2048
	global_load_dwordx4 v[156:159], v2, s[38:39] offset:3072
	s_add_u32 s38, s38, 0x800000
	s_addc_u32 s39, s39, 0
	s_waitcnt vmcnt(20)
	v_mul_f32_e32 v160, v63, v63
	v_fma_f32 v160, v62, v62, v160
	v_fma_f32 v160, v64, v64, v160
	v_fma_f32 v160, v65, v65, v160
	v_mul_f32_e32 v161, v67, v67
	v_fma_f32 v161, v66, v66, v161
	v_fma_f32 v161, v68, v68, v161
	v_fma_f32 v161, v69, v69, v161
	v_mul_f32_e32 v162, v71, v71
	v_fma_f32 v162, v70, v70, v162
	v_fma_f32 v162, v72, v72, v162
	v_fma_f32 v162, v73, v73, v162
	v_mul_f32_e32 v163, v75, v75
	v_fma_f32 v163, v74, v74, v163
	v_fma_f32 v163, v76, v76, v163
	v_fma_f32 v163, v77, v77, v163
	v_add_f32_e32 v164, v160, v161
	v_add_f32_e32 v164, v164, v162
	v_add_f32_e32 v164, v164, v163
	s_nop 1
	v_add_f32_dpp v164, v164, v164 quad_perm:[1,0,3,2] row_mask:0xf bank_mask:0xf bound_ctrl:1
	s_nop 1
	v_add_f32_dpp v164, v164, v164 quad_perm:[2,3,0,1] row_mask:0xf bank_mask:0xf bound_ctrl:1
	s_nop 1
	v_add_f32_dpp v164, v164, v164 row_half_mirror row_mask:0xf bank_mask:0xf bound_ctrl:1
	s_nop 1
	v_add_f32_dpp v164, v164, v164 row_mirror row_mask:0xf bank_mask:0xf bound_ctrl:1
	s_nop 1
	v_mov_b32_e32 v165, v164
	s_nop 1
	v_permlane16_swap_b32_e32 v164, v165
	s_nop 1
	v_add_f32_e32 v164, v164, v165
	v_mov_b32_e32 v165, v164
	s_nop 1
	v_permlane32_swap_b32_e32 v164, v165
	s_nop 1
	v_add_f32_e32 v164, v164, v165
	v_fmamk_f32 v164, v164, 0x3a800000, v176
	v_cmp_gt_f32_e32 vcc, s12, v164
	v_mul_f32_e32 v165, 0x4b800000, v164
	s_nop 0
	v_cndmask_b32_e32 v164, v164, v165, vcc
	v_rsq_f32_e32 v164, v164
	s_nop 0
	v_mul_f32_e32 v165, 0x45800000, v164
	v_cndmask_b32_e32 v166, v164, v165, vcc
	v_pk_mul_f32 v[62:63], v[62:63], v[166:167] op_sel_hi:[1,0]
	v_pk_mul_f32 v[64:65], v[64:65], v[166:167] op_sel_hi:[1,0]
	v_pk_mul_f32 v[62:63], v[4:5], v[62:63]
	v_pk_mul_f32 v[64:65], v[6:7], v[64:65]
	v_pk_add_f32 v[46:47], v[46:47], 1.0 op_sel_hi:[1,0]
	v_pk_add_f32 v[48:49], v[48:49], 1.0 op_sel_hi:[1,0]
	v_pk_fma_f32 v[62:63], v[46:47], v[62:63], v[30:31]
	v_pk_fma_f32 v[64:65], v[48:49], v[64:65], v[32:33]
	v_cvt_pk_bf16_f32 v168, v62, v63
	v_cvt_pk_bf16_f32 v169, v64, v65
	v_pk_mul_f32 v[66:67], v[66:67], v[166:167] op_sel_hi:[1,0]
	v_pk_mul_f32 v[68:69], v[68:69], v[166:167] op_sel_hi:[1,0]
	v_pk_mul_f32 v[66:67], v[8:9], v[66:67]
	v_pk_mul_f32 v[68:69], v[10:11], v[68:69]
	v_pk_add_f32 v[50:51], v[50:51], 1.0 op_sel_hi:[1,0]
	v_pk_add_f32 v[52:53], v[52:53], 1.0 op_sel_hi:[1,0]
	v_pk_fma_f32 v[66:67], v[50:51], v[66:67], v[34:35]
	v_pk_fma_f32 v[68:69], v[52:53], v[68:69], v[36:37]
	v_cvt_pk_bf16_f32 v170, v66, v67
	v_cvt_pk_bf16_f32 v171, v68, v69
	v_pk_mul_f32 v[70:71], v[70:71], v[166:167] op_sel_hi:[1,0]
	v_pk_mul_f32 v[72:73], v[72:73], v[166:167] op_sel_hi:[1,0]
	v_pk_mul_f32 v[70:71], v[12:13], v[70:71]
	v_pk_mul_f32 v[72:73], v[14:15], v[72:73]
	v_pk_add_f32 v[54:55], v[54:55], 1.0 op_sel_hi:[1,0]
	v_pk_add_f32 v[56:57], v[56:57], 1.0 op_sel_hi:[1,0]
	v_pk_fma_f32 v[70:71], v[54:55], v[70:71], v[38:39]
	v_pk_fma_f32 v[72:73], v[56:57], v[72:73], v[40:41]
	v_cvt_pk_bf16_f32 v172, v70, v71
	v_cvt_pk_bf16_f32 v173, v72, v73
	v_pk_mul_f32 v[74:75], v[74:75], v[166:167] op_sel_hi:[1,0]
	v_pk_mul_f32 v[76:77], v[76:77], v[166:167] op_sel_hi:[1,0]
	v_pk_mul_f32 v[74:75], v[16:17], v[74:75]
	v_pk_mul_f32 v[76:77], v[18:19], v[76:77]
	v_pk_add_f32 v[58:59], v[58:59], 1.0 op_sel_hi:[1,0]
	v_pk_add_f32 v[60:61], v[60:61], 1.0 op_sel_hi:[1,0]
	v_pk_fma_f32 v[74:75], v[58:59], v[74:75], v[42:43]
	v_pk_fma_f32 v[76:77], v[60:61], v[76:77], v[44:45]
	v_cvt_pk_bf16_f32 v174, v74, v75
	v_cvt_pk_bf16_f32 v175, v76, v77
	global_store_dwordx2 v1, v[168:169], s[42:43] offset:0
	global_store_dwordx2 v1, v[170:171], s[42:43] offset:512
	global_store_dwordx2 v1, v[172:173], s[42:43] offset:1024
	global_store_dwordx2 v1, v[174:175], s[42:43] offset:1536
	s_add_u32 s42, s42, 0x400000
	s_addc_u32 s43, s43, 0
	s_waitcnt vmcnt(20)
	v_mul_f32_e32 v160, v79, v79
	v_fma_f32 v160, v78, v78, v160
	v_fma_f32 v160, v80, v80, v160
	v_fma_f32 v160, v81, v81, v160
	v_mul_f32_e32 v161, v83, v83
	v_fma_f32 v161, v82, v82, v161
	v_fma_f32 v161, v84, v84, v161
	v_fma_f32 v161, v85, v85, v161
	v_mul_f32_e32 v162, v87, v87
	v_fma_f32 v162, v86, v86, v162
	v_fma_f32 v162, v88, v88, v162
	v_fma_f32 v162, v89, v89, v162
	v_mul_f32_e32 v163, v91, v91
	v_fma_f32 v163, v90, v90, v163
	v_fma_f32 v163, v92, v92, v163
	v_fma_f32 v163, v93, v93, v163
	v_add_f32_e32 v164, v160, v161
	v_add_f32_e32 v164, v164, v162
	v_add_f32_e32 v164, v164, v163
	s_nop 1
	v_add_f32_dpp v164, v164, v164 quad_perm:[1,0,3,2] row_mask:0xf bank_mask:0xf bound_ctrl:1
	s_nop 1
	v_add_f32_dpp v164, v164, v164 quad_perm:[2,3,0,1] row_mask:0xf bank_mask:0xf bound_ctrl:1
	s_nop 1
	v_add_f32_dpp v164, v164, v164 row_half_mirror row_mask:0xf bank_mask:0xf bound_ctrl:1
	s_nop 1
	v_add_f32_dpp v164, v164, v164 row_mirror row_mask:0xf bank_mask:0xf bound_ctrl:1
	s_nop 1
	v_mov_b32_e32 v165, v164
	s_nop 1
	v_permlane16_swap_b32_e32 v164, v165
	s_nop 1
	v_add_f32_e32 v164, v164, v165
	v_mov_b32_e32 v165, v164
	s_nop 1
	v_permlane32_swap_b32_e32 v164, v165
	s_nop 1
	v_add_f32_e32 v164, v164, v165
	v_fmamk_f32 v164, v164, 0x3a800000, v176
	v_cmp_gt_f32_e32 vcc, s12, v164
	v_mul_f32_e32 v165, 0x4b800000, v164
	s_nop 0
	v_cndmask_b32_e32 v164, v164, v165, vcc
	v_rsq_f32_e32 v164, v164
	s_nop 0
	v_mul_f32_e32 v165, 0x45800000, v164
	v_cndmask_b32_e32 v166, v164, v165, vcc
	v_pk_mul_f32 v[78:79], v[78:79], v[166:167] op_sel_hi:[1,0]
	v_pk_mul_f32 v[80:81], v[80:81], v[166:167] op_sel_hi:[1,0]
	v_pk_mul_f32 v[78:79], v[4:5], v[78:79]
	v_pk_mul_f32 v[80:81], v[6:7], v[80:81]
	v_pk_fma_f32 v[78:79], v[46:47], v[78:79], v[30:31]
	v_pk_fma_f32 v[80:81], v[48:49], v[80:81], v[32:33]
	v_cvt_pk_bf16_f32 v168, v78, v79
	v_cvt_pk_bf16_f32 v169, v80, v81
	v_pk_mul_f32 v[82:83], v[82:83], v[166:167] op_sel_hi:[1,0]
	v_pk_mul_f32 v[84:85], v[84:85], v[166:167] op_sel_hi:[1,0]
	v_pk_mul_f32 v[82:83], v[8:9], v[82:83]
	v_pk_mul_f32 v[84:85], v[10:11], v[84:85]
	v_pk_fma_f32 v[82:83], v[50:51], v[82:83], v[34:35]
	v_pk_fma_f32 v[84:85], v[52:53], v[84:85], v[36:37]
	v_cvt_pk_bf16_f32 v170, v82, v83
	v_cvt_pk_bf16_f32 v171, v84, v85
	v_pk_mul_f32 v[86:87], v[86:87], v[166:167] op_sel_hi:[1,0]
	v_pk_mul_f32 v[88:89], v[88:89], v[166:167] op_sel_hi:[1,0]
	v_pk_mul_f32 v[86:87], v[12:13], v[86:87]
	v_pk_mul_f32 v[88:89], v[14:15], v[88:89]
	v_pk_fma_f32 v[86:87], v[54:55], v[86:87], v[38:39]
	v_pk_fma_f32 v[88:89], v[56:57], v[88:89], v[40:41]
	v_cvt_pk_bf16_f32 v172, v86, v87
	v_cvt_pk_bf16_f32 v173, v88, v89
	v_pk_mul_f32 v[90:91], v[90:91], v[166:167] op_sel_hi:[1,0]
	v_pk_mul_f32 v[92:93], v[92:93], v[166:167] op_sel_hi:[1,0]
	v_pk_mul_f32 v[90:91], v[16:17], v[90:91]
	v_pk_mul_f32 v[92:93], v[18:19], v[92:93]
	v_pk_fma_f32 v[90:91], v[58:59], v[90:91], v[42:43]
	v_pk_fma_f32 v[92:93], v[60:61], v[92:93], v[44:45]
	v_cvt_pk_bf16_f32 v174, v90, v91
	v_cvt_pk_bf16_f32 v175, v92, v93
	global_store_dwordx2 v1, v[168:169], s[42:43] offset:0
	global_store_dwordx2 v1, v[170:171], s[42:43] offset:512
	global_store_dwordx2 v1, v[172:173], s[42:43] offset:1024
	global_store_dwordx2 v1, v[174:175], s[42:43] offset:1536
	s_add_u32 s42, s42, 0x400000
	s_addc_u32 s43, s43, 0
	s_lshr_b32 s48, s36, 12
	s_mul_i32 s48, s48, 0x3000
	s_add_u32 s44, s34, s48
	s_addc_u32 s45, s35, 0
	s_add_u32 s46, s44, 0x1000
	s_addc_u32 s47, s45, 0
	s_add_i32 s36, s36, 0x1000
	global_load_dwordx4 v[30:33], v2, s[44:45] offset:0
	global_load_dwordx4 v[34:37], v2, s[44:45] offset:1024
	global_load_dwordx4 v[38:41], v2, s[44:45] offset:2048
	global_load_dwordx4 v[42:45], v2, s[44:45] offset:3072
	global_load_dwordx4 v[46:49], v2, s[46:47] offset:0
	global_load_dwordx4 v[50:53], v2, s[46:47] offset:1024
	global_load_dwordx4 v[54:57], v2, s[46:47] offset:2048
	global_load_dwordx4 v[58:61], v2, s[46:47] offset:3072
	global_load_dwordx4 v[62:65], v2, s[38:39] offset:0
	global_load_dwordx4 v[66:69], v2, s[38:39] offset:1024
	global_load_dwordx4 v[70:73], v2, s[38:39] offset:2048
	global_load_dwordx4 v[74:77], v2, s[38:39] offset:3072
	s_add_u32 s38, s38, 0x800000
	s_addc_u32 s39, s39, 0
	global_load_dwordx4 v[78:81], v2, s[38:39] offset:0
	global_load_dwordx4 v[82:85], v2, s[38:39] offset:1024
	global_load_dwordx4 v[86:89], v2, s[38:39] offset:2048
	global_load_dwordx4 v[90:93], v2, s[38:39] offset:3072
	s_add_u32 s38, s38, 0x800000
	s_addc_u32 s39, s39, 0
	s_waitcnt vmcnt(28)
	v_mul_f32_e32 v160, v129, v129
	v_fma_f32 v160, v128, v128, v160
	v_fma_f32 v160, v130, v130, v160
	v_fma_f32 v160, v131, v131, v160
	v_mul_f32_e32 v161, v133, v133
	v_fma_f32 v161, v132, v132, v161
	v_fma_f32 v161, v134, v134, v161
	v_fma_f32 v161, v135, v135, v161
	v_mul_f32_e32 v162, v137, v137
	v_fma_f32 v162, v136, v136, v162
	v_fma_f32 v162, v138, v138, v162
	v_fma_f32 v162, v139, v139, v162
	v_mul_f32_e32 v163, v141, v141
	v_fma_f32 v163, v140, v140, v163
	v_fma_f32 v163, v142, v142, v163
	v_fma_f32 v163, v143, v143, v163
	v_add_f32_e32 v164, v160, v161
	v_add_f32_e32 v164, v164, v162
	v_add_f32_e32 v164, v164, v163
	s_nop 1
	v_add_f32_dpp v164, v164, v164 quad_perm:[1,0,3,2] row_mask:0xf bank_mask:0xf bound_ctrl:1
	s_nop 1
	v_add_f32_dpp v164, v164, v164 quad_perm:[2,3,0,1] row_mask:0xf bank_mask:0xf bound_ctrl:1
	s_nop 1
	v_add_f32_dpp v164, v164, v164 row_half_mirror row_mask:0xf bank_mask:0xf bound_ctrl:1
	s_nop 1
	v_add_f32_dpp v164, v164, v164 row_mirror row_mask:0xf bank_mask:0xf bound_ctrl:1
	s_nop 1
	v_mov_b32_e32 v165, v164
	s_nop 1
	v_permlane16_swap_b32_e32 v164, v165
	s_nop 1
	v_add_f32_e32 v164, v164, v165
	v_mov_b32_e32 v165, v164
	s_nop 1
	v_permlane32_swap_b32_e32 v164, v165
	s_nop 1
	v_add_f32_e32 v164, v164, v165
	v_fmamk_f32 v164, v164, 0x3a800000, v176
	v_cmp_gt_f32_e32 vcc, s12, v164
	v_mul_f32_e32 v165, 0x4b800000, v164
	s_nop 0
	v_cndmask_b32_e32 v164, v164, v165, vcc
	v_rsq_f32_e32 v164, v164
	s_nop 0
	v_mul_f32_e32 v165, 0x45800000, v164
	v_cndmask_b32_e32 v166, v164, v165, vcc
	v_pk_mul_f32 v[128:129], v[128:129], v[166:167] op_sel_hi:[1,0]
	v_pk_mul_f32 v[130:131], v[130:131], v[166:167] op_sel_hi:[1,0]
	v_pk_mul_f32 v[128:129], v[4:5], v[128:129]
	v_pk_mul_f32 v[130:131], v[6:7], v[130:131]
	v_pk_add_f32 v[112:113], v[112:113], 1.0 op_sel_hi:[1,0]
	v_pk_add_f32 v[114:115], v[114:115], 1.0 op_sel_hi:[1,0]
	v_pk_fma_f32 v[128:129], v[112:113], v[128:129], v[96:97]
	v_pk_fma_f32 v[130:131], v[114:115], v[130:131], v[98:99]
	v_cvt_pk_bf16_f32 v168, v128, v129
	v_cvt_pk_bf16_f32 v169, v130, v131
	v_pk_mul_f32 v[132:133], v[132:133], v[166:167] op_sel_hi:[1,0]
	v_pk_mul_f32 v[134:135], v[134:135], v[166:167] op_sel_hi:[1,0]
	v_pk_mul_f32 v[132:133], v[8:9], v[132:133]
	v_pk_mul_f32 v[134:135], v[10:11], v[134:135]
	v_pk_add_f32 v[116:117], v[116:117], 1.0 op_sel_hi:[1,0]
	v_pk_add_f32 v[118:119], v[118:119], 1.0 op_sel_hi:[1,0]
	v_pk_fma_f32 v[132:133], v[116:117], v[132:133], v[100:101]
	v_pk_fma_f32 v[134:135], v[118:119], v[134:135], v[102:103]
	v_cvt_pk_bf16_f32 v170, v132, v133
	v_cvt_pk_bf16_f32 v171, v134, v135
	v_pk_mul_f32 v[136:137], v[136:137], v[166:167] op_sel_hi:[1,0]
	v_pk_mul_f32 v[138:139], v[138:139], v[166:167] op_sel_hi:[1,0]
	v_pk_mul_f32 v[136:137], v[12:13], v[136:137]
	v_pk_mul_f32 v[138:139], v[14:15], v[138:139]
	v_pk_add_f32 v[120:121], v[120:121], 1.0 op_sel_hi:[1,0]
	v_pk_add_f32 v[122:123], v[122:123], 1.0 op_sel_hi:[1,0]
	v_pk_fma_f32 v[136:137], v[120:121], v[136:137], v[104:105]
	v_pk_fma_f32 v[138:139], v[122:123], v[138:139], v[106:107]
	v_cvt_pk_bf16_f32 v172, v136, v137
	v_cvt_pk_bf16_f32 v173, v138, v139
	v_pk_mul_f32 v[140:141], v[140:141], v[166:167] op_sel_hi:[1,0]
	v_pk_mul_f32 v[142:143], v[142:143], v[166:167] op_sel_hi:[1,0]
	v_pk_mul_f32 v[140:141], v[16:17], v[140:141]
	v_pk_mul_f32 v[142:143], v[18:19], v[142:143]
	v_pk_add_f32 v[124:125], v[124:125], 1.0 op_sel_hi:[1,0]
	v_pk_add_f32 v[126:127], v[126:127], 1.0 op_sel_hi:[1,0]
	v_pk_fma_f32 v[140:141], v[124:125], v[140:141], v[108:109]
	v_pk_fma_f32 v[142:143], v[126:127], v[142:143], v[110:111]
	v_cvt_pk_bf16_f32 v174, v140, v141
	v_cvt_pk_bf16_f32 v175, v142, v143
	global_store_dwordx2 v1, v[168:169], s[42:43] offset:0
	global_store_dwordx2 v1, v[170:171], s[42:43] offset:512
	global_store_dwordx2 v1, v[172:173], s[42:43] offset:1024
	global_store_dwordx2 v1, v[174:175], s[42:43] offset:1536
	s_add_u32 s42, s42, 0x400000
	s_addc_u32 s43, s43, 0
	s_waitcnt vmcnt(28)
	v_mul_f32_e32 v160, v145, v145
	v_fma_f32 v160, v144, v144, v160
	v_fma_f32 v160, v146, v146, v160
	v_fma_f32 v160, v147, v147, v160
	v_mul_f32_e32 v161, v149, v149
	v_fma_f32 v161, v148, v148, v161
	v_fma_f32 v161, v150, v150, v161
	v_fma_f32 v161, v151, v151, v161
	v_mul_f32_e32 v162, v153, v153
	v_fma_f32 v162, v152, v152, v162
	v_fma_f32 v162, v154, v154, v162
	v_fma_f32 v162, v155, v155, v162
	v_mul_f32_e32 v163, v157, v157
	v_fma_f32 v163, v156, v156, v163
	v_fma_f32 v163, v158, v158, v163
	v_fma_f32 v163, v159, v159, v163
	v_add_f32_e32 v164, v160, v161
	v_add_f32_e32 v164, v164, v162
	v_add_f32_e32 v164, v164, v163
	s_nop 1
	v_add_f32_dpp v164, v164, v164 quad_perm:[1,0,3,2] row_mask:0xf bank_mask:0xf bound_ctrl:1
	s_nop 1
	v_add_f32_dpp v164, v164, v164 quad_perm:[2,3,0,1] row_mask:0xf bank_mask:0xf bound_ctrl:1
	s_nop 1
	v_add_f32_dpp v164, v164, v164 row_half_mirror row_mask:0xf bank_mask:0xf bound_ctrl:1
	s_nop 1
	v_add_f32_dpp v164, v164, v164 row_mirror row_mask:0xf bank_mask:0xf bound_ctrl:1
	s_nop 1
	v_mov_b32_e32 v165, v164
	s_nop 1
	v_permlane16_swap_b32_e32 v164, v165
	s_nop 1
	v_add_f32_e32 v164, v164, v165
	v_mov_b32_e32 v165, v164
	s_nop 1
	v_permlane32_swap_b32_e32 v164, v165
	s_nop 1
	v_add_f32_e32 v164, v164, v165
	v_fmamk_f32 v164, v164, 0x3a800000, v176
	v_cmp_gt_f32_e32 vcc, s12, v164
	v_mul_f32_e32 v165, 0x4b800000, v164
	s_nop 0
	v_cndmask_b32_e32 v164, v164, v165, vcc
	v_rsq_f32_e32 v164, v164
	s_nop 0
	v_mul_f32_e32 v165, 0x45800000, v164
	v_cndmask_b32_e32 v166, v164, v165, vcc
	v_pk_mul_f32 v[144:145], v[144:145], v[166:167] op_sel_hi:[1,0]
	v_pk_mul_f32 v[146:147], v[146:147], v[166:167] op_sel_hi:[1,0]
	v_pk_mul_f32 v[144:145], v[4:5], v[144:145]
	v_pk_mul_f32 v[146:147], v[6:7], v[146:147]
	v_pk_fma_f32 v[144:145], v[112:113], v[144:145], v[96:97]
	v_pk_fma_f32 v[146:147], v[114:115], v[146:147], v[98:99]
	v_cvt_pk_bf16_f32 v168, v144, v145
	v_cvt_pk_bf16_f32 v169, v146, v147
	v_pk_mul_f32 v[148:149], v[148:149], v[166:167] op_sel_hi:[1,0]
	v_pk_mul_f32 v[150:151], v[150:151], v[166:167] op_sel_hi:[1,0]
	v_pk_mul_f32 v[148:149], v[8:9], v[148:149]
	v_pk_mul_f32 v[150:151], v[10:11], v[150:151]
	v_pk_fma_f32 v[148:149], v[116:117], v[148:149], v[100:101]
	v_pk_fma_f32 v[150:151], v[118:119], v[150:151], v[102:103]
	v_cvt_pk_bf16_f32 v170, v148, v149
	v_cvt_pk_bf16_f32 v171, v150, v151
	v_pk_mul_f32 v[152:153], v[152:153], v[166:167] op_sel_hi:[1,0]
	v_pk_mul_f32 v[154:155], v[154:155], v[166:167] op_sel_hi:[1,0]
	v_pk_mul_f32 v[152:153], v[12:13], v[152:153]
	v_pk_mul_f32 v[154:155], v[14:15], v[154:155]
	v_pk_fma_f32 v[152:153], v[120:121], v[152:153], v[104:105]
	v_pk_fma_f32 v[154:155], v[122:123], v[154:155], v[106:107]
	v_cvt_pk_bf16_f32 v172, v152, v153
	v_cvt_pk_bf16_f32 v173, v154, v155
	v_pk_mul_f32 v[156:157], v[156:157], v[166:167] op_sel_hi:[1,0]
	v_pk_mul_f32 v[158:159], v[158:159], v[166:167] op_sel_hi:[1,0]
	v_pk_mul_f32 v[156:157], v[16:17], v[156:157]
	v_pk_mul_f32 v[158:159], v[18:19], v[158:159]
	v_pk_fma_f32 v[156:157], v[124:125], v[156:157], v[108:109]
	v_pk_fma_f32 v[158:159], v[126:127], v[158:159], v[110:111]
	v_cvt_pk_bf16_f32 v174, v156, v157
	v_cvt_pk_bf16_f32 v175, v158, v159
	global_store_dwordx2 v1, v[168:169], s[42:43] offset:0
	global_store_dwordx2 v1, v[170:171], s[42:43] offset:512
	global_store_dwordx2 v1, v[172:173], s[42:43] offset:1024
	global_store_dwordx2 v1, v[174:175], s[42:43] offset:1536
	s_add_u32 s42, s42, 0x400000
	s_addc_u32 s43, s43, 0
	s_lshr_b32 s48, s36, 12
	s_mul_i32 s48, s48, 0x3000
	s_add_u32 s44, s34, s48
	s_addc_u32 s45, s35, 0
	s_add_u32 s46, s44, 0x1000
	s_addc_u32 s47, s45, 0
	s_add_i32 s36, s36, 0x1000
	global_load_dwordx4 v[96:99], v2, s[44:45] offset:0
	global_load_dwordx4 v[100:103], v2, s[44:45] offset:1024
	global_load_dwordx4 v[104:107], v2, s[44:45] offset:2048
	global_load_dwordx4 v[108:111], v2, s[44:45] offset:3072
	global_load_dwordx4 v[112:115], v2, s[46:47] offset:0
	global_load_dwordx4 v[116:119], v2, s[46:47] offset:1024
	global_load_dwordx4 v[120:123], v2, s[46:47] offset:2048
	global_load_dwordx4 v[124:127], v2, s[46:47] offset:3072
	global_load_dwordx4 v[128:131], v2, s[38:39] offset:0
	global_load_dwordx4 v[132:135], v2, s[38:39] offset:1024
	global_load_dwordx4 v[136:139], v2, s[38:39] offset:2048
	global_load_dwordx4 v[140:143], v2, s[38:39] offset:3072
	s_add_u32 s38, s38, 0x800000
	s_addc_u32 s39, s39, 0
	global_load_dwordx4 v[144:147], v2, s[38:39] offset:0
	global_load_dwordx4 v[148:151], v2, s[38:39] offset:1024
	global_load_dwordx4 v[152:155], v2, s[38:39] offset:2048
	global_load_dwordx4 v[156:159], v2, s[38:39] offset:3072
	s_add_u32 s38, s38, 0x800000
	s_addc_u32 s39, s39, 0
	s_waitcnt vmcnt(28)
	v_mul_f32_e32 v160, v63, v63
	v_fma_f32 v160, v62, v62, v160
	v_fma_f32 v160, v64, v64, v160
	v_fma_f32 v160, v65, v65, v160
	v_mul_f32_e32 v161, v67, v67
	v_fma_f32 v161, v66, v66, v161
	v_fma_f32 v161, v68, v68, v161
	v_fma_f32 v161, v69, v69, v161
	v_mul_f32_e32 v162, v71, v71
	v_fma_f32 v162, v70, v70, v162
	v_fma_f32 v162, v72, v72, v162
	v_fma_f32 v162, v73, v73, v162
	v_mul_f32_e32 v163, v75, v75
	v_fma_f32 v163, v74, v74, v163
	v_fma_f32 v163, v76, v76, v163
	v_fma_f32 v163, v77, v77, v163
	v_add_f32_e32 v164, v160, v161
	v_add_f32_e32 v164, v164, v162
	v_add_f32_e32 v164, v164, v163
	s_nop 1
	v_add_f32_dpp v164, v164, v164 quad_perm:[1,0,3,2] row_mask:0xf bank_mask:0xf bound_ctrl:1
	s_nop 1
	v_add_f32_dpp v164, v164, v164 quad_perm:[2,3,0,1] row_mask:0xf bank_mask:0xf bound_ctrl:1
	s_nop 1
	v_add_f32_dpp v164, v164, v164 row_half_mirror row_mask:0xf bank_mask:0xf bound_ctrl:1
	s_nop 1
	v_add_f32_dpp v164, v164, v164 row_mirror row_mask:0xf bank_mask:0xf bound_ctrl:1
	s_nop 1
	v_mov_b32_e32 v165, v164
	s_nop 1
	v_permlane16_swap_b32_e32 v164, v165
	s_nop 1
	v_add_f32_e32 v164, v164, v165
	v_mov_b32_e32 v165, v164
	s_nop 1
	v_permlane32_swap_b32_e32 v164, v165
	s_nop 1
	v_add_f32_e32 v164, v164, v165
	v_fmamk_f32 v164, v164, 0x3a800000, v176
	v_cmp_gt_f32_e32 vcc, s12, v164
	v_mul_f32_e32 v165, 0x4b800000, v164
	s_nop 0
	v_cndmask_b32_e32 v164, v164, v165, vcc
	v_rsq_f32_e32 v164, v164
	s_nop 0
	v_mul_f32_e32 v165, 0x45800000, v164
	v_cndmask_b32_e32 v166, v164, v165, vcc
	v_pk_mul_f32 v[62:63], v[62:63], v[166:167] op_sel_hi:[1,0]
	v_pk_mul_f32 v[64:65], v[64:65], v[166:167] op_sel_hi:[1,0]
	v_pk_mul_f32 v[62:63], v[4:5], v[62:63]
	v_pk_mul_f32 v[64:65], v[6:7], v[64:65]
	v_pk_add_f32 v[46:47], v[46:47], 1.0 op_sel_hi:[1,0]
	v_pk_add_f32 v[48:49], v[48:49], 1.0 op_sel_hi:[1,0]
	v_pk_fma_f32 v[62:63], v[46:47], v[62:63], v[30:31]
	v_pk_fma_f32 v[64:65], v[48:49], v[64:65], v[32:33]
	v_cvt_pk_bf16_f32 v168, v62, v63
	v_cvt_pk_bf16_f32 v169, v64, v65
	v_pk_mul_f32 v[66:67], v[66:67], v[166:167] op_sel_hi:[1,0]
	v_pk_mul_f32 v[68:69], v[68:69], v[166:167] op_sel_hi:[1,0]
	v_pk_mul_f32 v[66:67], v[8:9], v[66:67]
	v_pk_mul_f32 v[68:69], v[10:11], v[68:69]
	v_pk_add_f32 v[50:51], v[50:51], 1.0 op_sel_hi:[1,0]
	v_pk_add_f32 v[52:53], v[52:53], 1.0 op_sel_hi:[1,0]
	v_pk_fma_f32 v[66:67], v[50:51], v[66:67], v[34:35]
	v_pk_fma_f32 v[68:69], v[52:53], v[68:69], v[36:37]
	v_cvt_pk_bf16_f32 v170, v66, v67
	v_cvt_pk_bf16_f32 v171, v68, v69
	v_pk_mul_f32 v[70:71], v[70:71], v[166:167] op_sel_hi:[1,0]
	v_pk_mul_f32 v[72:73], v[72:73], v[166:167] op_sel_hi:[1,0]
	v_pk_mul_f32 v[70:71], v[12:13], v[70:71]
	v_pk_mul_f32 v[72:73], v[14:15], v[72:73]
	v_pk_add_f32 v[54:55], v[54:55], 1.0 op_sel_hi:[1,0]
	v_pk_add_f32 v[56:57], v[56:57], 1.0 op_sel_hi:[1,0]
	v_pk_fma_f32 v[70:71], v[54:55], v[70:71], v[38:39]
	v_pk_fma_f32 v[72:73], v[56:57], v[72:73], v[40:41]
	v_cvt_pk_bf16_f32 v172, v70, v71
	v_cvt_pk_bf16_f32 v173, v72, v73
	v_pk_mul_f32 v[74:75], v[74:75], v[166:167] op_sel_hi:[1,0]
	v_pk_mul_f32 v[76:77], v[76:77], v[166:167] op_sel_hi:[1,0]
	v_pk_mul_f32 v[74:75], v[16:17], v[74:75]
	v_pk_mul_f32 v[76:77], v[18:19], v[76:77]
	v_pk_add_f32 v[58:59], v[58:59], 1.0 op_sel_hi:[1,0]
	v_pk_add_f32 v[60:61], v[60:61], 1.0 op_sel_hi:[1,0]
	v_pk_fma_f32 v[74:75], v[58:59], v[74:75], v[42:43]
	v_pk_fma_f32 v[76:77], v[60:61], v[76:77], v[44:45]
	v_cvt_pk_bf16_f32 v174, v74, v75
	v_cvt_pk_bf16_f32 v175, v76, v77
	global_store_dwordx2 v1, v[168:169], s[42:43] offset:0
	global_store_dwordx2 v1, v[170:171], s[42:43] offset:512
	global_store_dwordx2 v1, v[172:173], s[42:43] offset:1024
	global_store_dwordx2 v1, v[174:175], s[42:43] offset:1536
	s_add_u32 s42, s42, 0x400000
	s_addc_u32 s43, s43, 0
	s_waitcnt vmcnt(28)
	v_mul_f32_e32 v160, v79, v79
	v_fma_f32 v160, v78, v78, v160
	v_fma_f32 v160, v80, v80, v160
	v_fma_f32 v160, v81, v81, v160
	v_mul_f32_e32 v161, v83, v83
	v_fma_f32 v161, v82, v82, v161
	v_fma_f32 v161, v84, v84, v161
	v_fma_f32 v161, v85, v85, v161
	v_mul_f32_e32 v162, v87, v87
	v_fma_f32 v162, v86, v86, v162
	v_fma_f32 v162, v88, v88, v162
	v_fma_f32 v162, v89, v89, v162
	v_mul_f32_e32 v163, v91, v91
	v_fma_f32 v163, v90, v90, v163
	v_fma_f32 v163, v92, v92, v163
	v_fma_f32 v163, v93, v93, v163
	v_add_f32_e32 v164, v160, v161
	v_add_f32_e32 v164, v164, v162
	v_add_f32_e32 v164, v164, v163
	s_nop 1
	v_add_f32_dpp v164, v164, v164 quad_perm:[1,0,3,2] row_mask:0xf bank_mask:0xf bound_ctrl:1
	s_nop 1
	v_add_f32_dpp v164, v164, v164 quad_perm:[2,3,0,1] row_mask:0xf bank_mask:0xf bound_ctrl:1
	s_nop 1
	v_add_f32_dpp v164, v164, v164 row_half_mirror row_mask:0xf bank_mask:0xf bound_ctrl:1
	s_nop 1
	v_add_f32_dpp v164, v164, v164 row_mirror row_mask:0xf bank_mask:0xf bound_ctrl:1
	s_nop 1
	v_mov_b32_e32 v165, v164
	s_nop 1
	v_permlane16_swap_b32_e32 v164, v165
	s_nop 1
	v_add_f32_e32 v164, v164, v165
	v_mov_b32_e32 v165, v164
	s_nop 1
	v_permlane32_swap_b32_e32 v164, v165
	s_nop 1
	v_add_f32_e32 v164, v164, v165
	v_fmamk_f32 v164, v164, 0x3a800000, v176
	v_cmp_gt_f32_e32 vcc, s12, v164
	v_mul_f32_e32 v165, 0x4b800000, v164
	s_nop 0
	v_cndmask_b32_e32 v164, v164, v165, vcc
	v_rsq_f32_e32 v164, v164
	s_nop 0
	v_mul_f32_e32 v165, 0x45800000, v164
	v_cndmask_b32_e32 v166, v164, v165, vcc
	v_pk_mul_f32 v[78:79], v[78:79], v[166:167] op_sel_hi:[1,0]
	v_pk_mul_f32 v[80:81], v[80:81], v[166:167] op_sel_hi:[1,0]
	v_pk_mul_f32 v[78:79], v[4:5], v[78:79]
	v_pk_mul_f32 v[80:81], v[6:7], v[80:81]
	v_pk_fma_f32 v[78:79], v[46:47], v[78:79], v[30:31]
	v_pk_fma_f32 v[80:81], v[48:49], v[80:81], v[32:33]
	v_cvt_pk_bf16_f32 v168, v78, v79
	v_cvt_pk_bf16_f32 v169, v80, v81
	v_pk_mul_f32 v[82:83], v[82:83], v[166:167] op_sel_hi:[1,0]
	v_pk_mul_f32 v[84:85], v[84:85], v[166:167] op_sel_hi:[1,0]
	v_pk_mul_f32 v[82:83], v[8:9], v[82:83]
	v_pk_mul_f32 v[84:85], v[10:11], v[84:85]
	v_pk_fma_f32 v[82:83], v[50:51], v[82:83], v[34:35]
	v_pk_fma_f32 v[84:85], v[52:53], v[84:85], v[36:37]
	v_cvt_pk_bf16_f32 v170, v82, v83
	v_cvt_pk_bf16_f32 v171, v84, v85
	v_pk_mul_f32 v[86:87], v[86:87], v[166:167] op_sel_hi:[1,0]
	v_pk_mul_f32 v[88:89], v[88:89], v[166:167] op_sel_hi:[1,0]
	v_pk_mul_f32 v[86:87], v[12:13], v[86:87]
	v_pk_mul_f32 v[88:89], v[14:15], v[88:89]
	v_pk_fma_f32 v[86:87], v[54:55], v[86:87], v[38:39]
	v_pk_fma_f32 v[88:89], v[56:57], v[88:89], v[40:41]
	v_cvt_pk_bf16_f32 v172, v86, v87
	v_cvt_pk_bf16_f32 v173, v88, v89
	v_pk_mul_f32 v[90:91], v[90:91], v[166:167] op_sel_hi:[1,0]
	v_pk_mul_f32 v[92:93], v[92:93], v[166:167] op_sel_hi:[1,0]
	v_pk_mul_f32 v[90:91], v[16:17], v[90:91]
	v_pk_mul_f32 v[92:93], v[18:19], v[92:93]
	v_pk_fma_f32 v[90:91], v[58:59], v[90:91], v[42:43]
	v_pk_fma_f32 v[92:93], v[60:61], v[92:93], v[44:45]
	v_cvt_pk_bf16_f32 v174, v90, v91
	v_cvt_pk_bf16_f32 v175, v92, v93
	global_store_dwordx2 v1, v[168:169], s[42:43] offset:0
	global_store_dwordx2 v1, v[170:171], s[42:43] offset:512
	global_store_dwordx2 v1, v[172:173], s[42:43] offset:1024
	global_store_dwordx2 v1, v[174:175], s[42:43] offset:1536
	s_add_u32 s42, s42, 0x400000
	s_addc_u32 s43, s43, 0
	s_waitcnt vmcnt(12)
	v_mul_f32_e32 v160, v129, v129
	v_fma_f32 v160, v128, v128, v160
	v_fma_f32 v160, v130, v130, v160
	v_fma_f32 v160, v131, v131, v160
	v_mul_f32_e32 v161, v133, v133
	v_fma_f32 v161, v132, v132, v161
	v_fma_f32 v161, v134, v134, v161
	v_fma_f32 v161, v135, v135, v161
	v_mul_f32_e32 v162, v137, v137
	v_fma_f32 v162, v136, v136, v162
	v_fma_f32 v162, v138, v138, v162
	v_fma_f32 v162, v139, v139, v162
	v_mul_f32_e32 v163, v141, v141
	v_fma_f32 v163, v140, v140, v163
	v_fma_f32 v163, v142, v142, v163
	v_fma_f32 v163, v143, v143, v163
	v_add_f32_e32 v164, v160, v161
	v_add_f32_e32 v164, v164, v162
	v_add_f32_e32 v164, v164, v163
	s_nop 1
	v_add_f32_dpp v164, v164, v164 quad_perm:[1,0,3,2] row_mask:0xf bank_mask:0xf bound_ctrl:1
	s_nop 1
	v_add_f32_dpp v164, v164, v164 quad_perm:[2,3,0,1] row_mask:0xf bank_mask:0xf bound_ctrl:1
	s_nop 1
	v_add_f32_dpp v164, v164, v164 row_half_mirror row_mask:0xf bank_mask:0xf bound_ctrl:1
	s_nop 1
	v_add_f32_dpp v164, v164, v164 row_mirror row_mask:0xf bank_mask:0xf bound_ctrl:1
	s_nop 1
	v_mov_b32_e32 v165, v164
	s_nop 1
	v_permlane16_swap_b32_e32 v164, v165
	s_nop 1
	v_add_f32_e32 v164, v164, v165
	v_mov_b32_e32 v165, v164
	s_nop 1
	v_permlane32_swap_b32_e32 v164, v165
	s_nop 1
	v_add_f32_e32 v164, v164, v165
	v_fmamk_f32 v164, v164, 0x3a800000, v176
	v_cmp_gt_f32_e32 vcc, s12, v164
	v_mul_f32_e32 v165, 0x4b800000, v164
	s_nop 0
	v_cndmask_b32_e32 v164, v164, v165, vcc
	v_rsq_f32_e32 v164, v164
	s_nop 0
	v_mul_f32_e32 v165, 0x45800000, v164
	v_cndmask_b32_e32 v166, v164, v165, vcc
	v_pk_mul_f32 v[128:129], v[128:129], v[166:167] op_sel_hi:[1,0]
	v_pk_mul_f32 v[130:131], v[130:131], v[166:167] op_sel_hi:[1,0]
	v_pk_mul_f32 v[128:129], v[4:5], v[128:129]
	v_pk_mul_f32 v[130:131], v[6:7], v[130:131]
	v_pk_add_f32 v[112:113], v[112:113], 1.0 op_sel_hi:[1,0]
	v_pk_add_f32 v[114:115], v[114:115], 1.0 op_sel_hi:[1,0]
	v_pk_fma_f32 v[128:129], v[112:113], v[128:129], v[96:97]
	v_pk_fma_f32 v[130:131], v[114:115], v[130:131], v[98:99]
	v_cvt_pk_bf16_f32 v168, v128, v129
	v_cvt_pk_bf16_f32 v169, v130, v131
	v_pk_mul_f32 v[132:133], v[132:133], v[166:167] op_sel_hi:[1,0]
	v_pk_mul_f32 v[134:135], v[134:135], v[166:167] op_sel_hi:[1,0]
	v_pk_mul_f32 v[132:133], v[8:9], v[132:133]
	v_pk_mul_f32 v[134:135], v[10:11], v[134:135]
	v_pk_add_f32 v[116:117], v[116:117], 1.0 op_sel_hi:[1,0]
	v_pk_add_f32 v[118:119], v[118:119], 1.0 op_sel_hi:[1,0]
	v_pk_fma_f32 v[132:133], v[116:117], v[132:133], v[100:101]
	v_pk_fma_f32 v[134:135], v[118:119], v[134:135], v[102:103]
	v_cvt_pk_bf16_f32 v170, v132, v133
	v_cvt_pk_bf16_f32 v171, v134, v135
	v_pk_mul_f32 v[136:137], v[136:137], v[166:167] op_sel_hi:[1,0]
	v_pk_mul_f32 v[138:139], v[138:139], v[166:167] op_sel_hi:[1,0]
	v_pk_mul_f32 v[136:137], v[12:13], v[136:137]
	v_pk_mul_f32 v[138:139], v[14:15], v[138:139]
	v_pk_add_f32 v[120:121], v[120:121], 1.0 op_sel_hi:[1,0]
	v_pk_add_f32 v[122:123], v[122:123], 1.0 op_sel_hi:[1,0]
	v_pk_fma_f32 v[136:137], v[120:121], v[136:137], v[104:105]
	v_pk_fma_f32 v[138:139], v[122:123], v[138:139], v[106:107]
	v_cvt_pk_bf16_f32 v172, v136, v137
	v_cvt_pk_bf16_f32 v173, v138, v139
	v_pk_mul_f32 v[140:141], v[140:141], v[166:167] op_sel_hi:[1,0]
	v_pk_mul_f32 v[142:143], v[142:143], v[166:167] op_sel_hi:[1,0]
	v_pk_mul_f32 v[140:141], v[16:17], v[140:141]
	v_pk_mul_f32 v[142:143], v[18:19], v[142:143]
	v_pk_add_f32 v[124:125], v[124:125], 1.0 op_sel_hi:[1,0]
	v_pk_add_f32 v[126:127], v[126:127], 1.0 op_sel_hi:[1,0]
	v_pk_fma_f32 v[140:141], v[124:125], v[140:141], v[108:109]
	v_pk_fma_f32 v[142:143], v[126:127], v[142:143], v[110:111]
	v_cvt_pk_bf16_f32 v174, v140, v141
	v_cvt_pk_bf16_f32 v175, v142, v143
	global_store_dwordx2 v1, v[168:169], s[42:43] offset:0
	global_store_dwordx2 v1, v[170:171], s[42:43] offset:512
	global_store_dwordx2 v1, v[172:173], s[42:43] offset:1024
	global_store_dwordx2 v1, v[174:175], s[42:43] offset:1536
	s_add_u32 s42, s42, 0x400000
	s_addc_u32 s43, s43, 0
	s_waitcnt vmcnt(12)
	v_mul_f32_e32 v160, v145, v145
	v_fma_f32 v160, v144, v144, v160
	v_fma_f32 v160, v146, v146, v160
	v_fma_f32 v160, v147, v147, v160
	v_mul_f32_e32 v161, v149, v149
	v_fma_f32 v161, v148, v148, v161
	v_fma_f32 v161, v150, v150, v161
	v_fma_f32 v161, v151, v151, v161
	v_mul_f32_e32 v162, v153, v153
	v_fma_f32 v162, v152, v152, v162
	v_fma_f32 v162, v154, v154, v162
	v_fma_f32 v162, v155, v155, v162
	v_mul_f32_e32 v163, v157, v157
	v_fma_f32 v163, v156, v156, v163
	v_fma_f32 v163, v158, v158, v163
	v_fma_f32 v163, v159, v159, v163
	v_add_f32_e32 v164, v160, v161
	v_add_f32_e32 v164, v164, v162
	v_add_f32_e32 v164, v164, v163
	s_nop 1
	v_add_f32_dpp v164, v164, v164 quad_perm:[1,0,3,2] row_mask:0xf bank_mask:0xf bound_ctrl:1
	s_nop 1
	v_add_f32_dpp v164, v164, v164 quad_perm:[2,3,0,1] row_mask:0xf bank_mask:0xf bound_ctrl:1
	s_nop 1
	v_add_f32_dpp v164, v164, v164 row_half_mirror row_mask:0xf bank_mask:0xf bound_ctrl:1
	s_nop 1
	v_add_f32_dpp v164, v164, v164 row_mirror row_mask:0xf bank_mask:0xf bound_ctrl:1
	s_nop 1
	v_mov_b32_e32 v165, v164
	s_nop 1
	v_permlane16_swap_b32_e32 v164, v165
	s_nop 1
	v_add_f32_e32 v164, v164, v165
	v_mov_b32_e32 v165, v164
	s_nop 1
	v_permlane32_swap_b32_e32 v164, v165
	s_nop 1
	v_add_f32_e32 v164, v164, v165
	v_fmamk_f32 v164, v164, 0x3a800000, v176
	v_cmp_gt_f32_e32 vcc, s12, v164
	v_mul_f32_e32 v165, 0x4b800000, v164
	s_nop 0
	v_cndmask_b32_e32 v164, v164, v165, vcc
	v_rsq_f32_e32 v164, v164
	s_nop 0
	v_mul_f32_e32 v165, 0x45800000, v164
	v_cndmask_b32_e32 v166, v164, v165, vcc
	v_pk_mul_f32 v[144:145], v[144:145], v[166:167] op_sel_hi:[1,0]
	v_pk_mul_f32 v[146:147], v[146:147], v[166:167] op_sel_hi:[1,0]
	v_pk_mul_f32 v[144:145], v[4:5], v[144:145]
	v_pk_mul_f32 v[146:147], v[6:7], v[146:147]
	v_pk_fma_f32 v[144:145], v[112:113], v[144:145], v[96:97]
	v_pk_fma_f32 v[146:147], v[114:115], v[146:147], v[98:99]
	v_cvt_pk_bf16_f32 v168, v144, v145
	v_cvt_pk_bf16_f32 v169, v146, v147
	v_pk_mul_f32 v[148:149], v[148:149], v[166:167] op_sel_hi:[1,0]
	v_pk_mul_f32 v[150:151], v[150:151], v[166:167] op_sel_hi:[1,0]
	v_pk_mul_f32 v[148:149], v[8:9], v[148:149]
	v_pk_mul_f32 v[150:151], v[10:11], v[150:151]
	v_pk_fma_f32 v[148:149], v[116:117], v[148:149], v[100:101]
	v_pk_fma_f32 v[150:151], v[118:119], v[150:151], v[102:103]
	v_cvt_pk_bf16_f32 v170, v148, v149
	v_cvt_pk_bf16_f32 v171, v150, v151
	v_pk_mul_f32 v[152:153], v[152:153], v[166:167] op_sel_hi:[1,0]
	v_pk_mul_f32 v[154:155], v[154:155], v[166:167] op_sel_hi:[1,0]
	v_pk_mul_f32 v[152:153], v[12:13], v[152:153]
	v_pk_mul_f32 v[154:155], v[14:15], v[154:155]
	v_pk_fma_f32 v[152:153], v[120:121], v[152:153], v[104:105]
	v_pk_fma_f32 v[154:155], v[122:123], v[154:155], v[106:107]
	v_cvt_pk_bf16_f32 v172, v152, v153
	v_cvt_pk_bf16_f32 v173, v154, v155
	v_pk_mul_f32 v[156:157], v[156:157], v[166:167] op_sel_hi:[1,0]
	v_pk_mul_f32 v[158:159], v[158:159], v[166:167] op_sel_hi:[1,0]
	v_pk_mul_f32 v[156:157], v[16:17], v[156:157]
	v_pk_mul_f32 v[158:159], v[18:19], v[158:159]
	v_pk_fma_f32 v[156:157], v[124:125], v[156:157], v[108:109]
	v_pk_fma_f32 v[158:159], v[126:127], v[158:159], v[110:111]
	v_cvt_pk_bf16_f32 v174, v156, v157
	v_cvt_pk_bf16_f32 v175, v158, v159
	global_store_dwordx2 v1, v[168:169], s[42:43] offset:0
	global_store_dwordx2 v1, v[170:171], s[42:43] offset:512
	global_store_dwordx2 v1, v[172:173], s[42:43] offset:1024
	global_store_dwordx2 v1, v[174:175], s[42:43] offset:1536
	s_add_u32 s42, s42, 0x400000
	s_addc_u32 s43, s43, 0
	s_branch .LBB0_200
